# attention QK: next step's K/Q fragment LDS reads issued before the current step's first MFMA
# speedup vs baseline: 1.0131x; 1.0019x over previous
; template <int G> __device__ __forceinline__ void fin_gap(f32x16& P0, f32x16& P1, float (&sacc)[4], unsigned (&cv)[16], u32x4 (&pw)[4]) {
;   if constexpr (G < 16) { P1[G] = __builtin_amdgcn_exp2f(P1[G]); sacc[G & 3] += P0[G]; }
;   else { constexpr int r = 2 * (G - 16); sacc[r & 3] += P1[r]; sacc[(r + 1) & 3] += P1[r + 1]; }
;   if constexpr (G < 4) cv[G] = cvtpk_c(P0[2 * G], P0[2 * G + 1]);
;   else if constexpr (G >= 6 && G < 10) { constexpr int i = G - 2; cv[i] = cvtpk_c(P0[2 * i], P0[2 * i + 1]); }
;   else if constexpr (G >= 12 && G < 16) { constexpr int i = G - 4, j = i - 8; cv[i] = cvtpk_c(P1[2 * j], P1[2 * j + 1]); }
;   else if constexpr (G >= 18 && G < 22) { constexpr int i = G - 6, j = i - 8; cv[i] = cvtpk_c(P1[2 * j], P1[2 * j + 1]); }
;   if constexpr (G == 4 || G == 10 || G == 16 || G == 22) { constexpr int q = (G - 4) / 6; auto r0 = __builtin_amdgcn_permlane32_swap(cv[4 * q], cv[4 * q + 2], false, false); pw[q].x = r0[0]; pw[q].z = r0[1]; }
;   if constexpr (G == 5 || G == 11 || G == 17 || G == 23) { constexpr int q = (G - 5) / 6; auto r1 = __builtin_amdgcn_permlane32_swap(cv[4 * q + 1], cv[4 * q + 3], false, false); pw[q].y = r1[0]; pw[q].w = r1[1]; }
; }
.LBB0_754:
	ds_read_b128 v[70:73], v178 offset:57344
	ds_read_b128 v[74:77], v178 offset:61440
	s_waitcnt lgkmcnt(0)
	ds_read_b128 v[134:137], v179 offset:57344
	ds_read_b128 v[186:189], v179 offset:61440
	v_mfma_f32_32x32x16_bf16 v[84:99], v[70:73], v[126:129], 0
	v_exp_f32_e32 v210, v130
	v_add_f32_e32 v185, 0, v68
	v_cvt_pk_bf16_f32 v130, v68, v1
	v_mfma_f32_32x32x16_bf16 v[68:83], v[74:77], v[126:129], 0
	v_exp_f32_e32 v211, v131
	v_add_f32_e32 v1, 0, v1
	v_cvt_pk_bf16_f32 v131, v112, v113
	s_waitcnt lgkmcnt(0)
	ds_read_b128 v[190:193], v177 offset:57344
	ds_read_b128 v[194:197], v177 offset:61440
	v_mfma_f32_32x32x16_bf16 v[84:99], v[134:137], v[122:125], v[84:99]
	v_exp_f32_e32 v212, v132
	v_add_f32_e32 v202, 0, v112
	v_cvt_pk_bf16_f32 v132, v110, v111
	v_mfma_f32_32x32x16_bf16 v[68:83], v[186:189], v[122:125], v[68:83]
	v_exp_f32_e32 v213, v133
	v_add_f32_e32 v203, 0, v113
	v_cvt_pk_bf16_f32 v133, v108, v109
	s_waitcnt lgkmcnt(0)
	ds_read_b128 v[134:137], v176 offset:57344
	ds_read_b128 v[198:201], v176 offset:61440
	v_mfma_f32_32x32x16_bf16 v[84:99], v[190:193], v[118:121], v[84:99]
	v_add_f32_e32 v189, v110, v185
	v_permlane32_swap_b32_e32 v130, v132
	v_exp_f32_e32 v214, v160
	v_mfma_f32_32x32x16_bf16 v[68:83], v[194:197], v[118:121], v[68:83]
	v_add_f32_e32 v1, v111, v1
	v_permlane32_swap_b32_e32 v131, v133
	v_exp_f32_e32 v215, v161
	s_waitcnt lgkmcnt(0)
	v_add_u32_e32 v185, v181, v172
	v_add_u32_e32 v186, v182, v172
	ds_read_b128 v[110:113], v185
	ds_read_b128 v[190:193], v186
	v_mfma_f32_32x32x16_bf16 v[84:99], v[134:137], v[114:117], v[84:99]
	v_add_f32_e32 v217, v108, v202
	v_cvt_pk_bf16_f32 v108, v106, v107
	v_exp_f32_e32 v216, v158
	v_mfma_f32_32x32x16_bf16 v[68:83], v[198:201], v[114:117], v[68:83]
	v_add_f32_e32 v219, v109, v203
	v_cvt_pk_bf16_f32 v109, v104, v105
	v_exp_f32_e32 v218, v159
	s_waitcnt lgkmcnt(0)
	v_add_u32_e32 v187, v181, v173
	v_add_u32_e32 v188, v182, v173
	ds_read_b128 v[134:137], v187
	ds_read_b128 v[158:161], v188
	v_mfma_f32_32x32x16_bf16 v[84:99], v[110:113], v[238:241], v[84:99]
	v_cvt_pk_bf16_f32 v110, v102, v103
	v_exp_f32_e32 v220, v156
	v_add_f32_e32 v112, v106, v189
	v_mfma_f32_32x32x16_bf16 v[68:83], v[190:193], v[238:241], v[68:83]
	v_add_f32_e32 v1, v107, v1
	v_cvt_pk_bf16_f32 v111, v100, v101
	v_exp_f32_e32 v113, v157
	s_waitcnt lgkmcnt(0)
	v_add_u32_e32 v189, v181, v174
	v_add_u32_e32 v190, v182, v174
	ds_read_b128 v[194:197], v189
	ds_read_b128 v[202:205], v190
	v_mfma_f32_32x32x16_bf16 v[84:99], v[134:137], v[242:245], v[84:99]
	v_permlane32_swap_b32_e32 v108, v110
	v_exp_f32_e32 v221, v154
	v_add_f32_e32 v217, v104, v217
	v_mfma_f32_32x32x16_bf16 v[68:83], v[158:161], v[242:245], v[68:83]
	v_permlane32_swap_b32_e32 v109, v111
	v_exp_f32_e32 v222, v155
	v_add_f32_e32 v219, v105, v219
	s_waitcnt lgkmcnt(0)
	v_add_u32_e32 v191, v181, v175
	v_add_u32_e32 v192, v182, v175
	ds_read_b128 v[104:107], v191
	ds_read_b128 v[134:137], v192
	v_mfma_f32_32x32x16_bf16 v[84:99], v[194:197], v[248:251], v[84:99]
	v_add_f32_e32 v112, v102, v112
	v_cvt_pk_bf16_f32 v102, v210, v211
	v_exp_f32_e32 v223, v152
	v_mfma_f32_32x32x16_bf16 v[68:83], v[202:205], v[248:251], v[68:83]
	v_add_f32_e32 v1, v103, v1
	v_cvt_pk_bf16_f32 v103, v212, v213
	v_exp_f32_e32 v226, v153
	s_waitcnt lgkmcnt(0)
	v_add_u32_e32 v193, v183, v172
	v_add_u32_e32 v194, v184, v172
	ds_read_b128 v[158:161], v193
	ds_read_b128 v[198:201], v194
	ds_read_b128 v[202:205], v171 offset:4096
	v_mfma_f32_32x32x16_bf16 v[84:99], v[104:107], v[252:255], v[84:99]
	v_cvt_pk_bf16_f32 v104, v214, v215
	v_exp_f32_e32 v227, v150
	v_add_f32_e32 v100, v100, v217
	v_mfma_f32_32x32x16_bf16 v[68:83], v[134:137], v[252:255], v[68:83]
	v_cvt_pk_bf16_f32 v105, v216, v218
	v_exp_f32_e32 v106, v151
	v_add_f32_e32 v101, v101, v219
	s_waitcnt lgkmcnt(0)
	v_add_u32_e32 v195, v183, v173
	v_add_u32_e32 v196, v184, v173
	ds_read_b128 v[134:137], v195
	ds_read_b128 v[150:153], v196
	ds_read_b128 v[154:157], v170 offset:4096
	v_mfma_f32_32x32x16_bf16 v[84:99], v[158:161], v[202:205], v[84:99]
	v_add_f32_e32 v1, v211, v1
	v_permlane32_swap_b32_e32 v102, v104
	v_add_f32_e32 v107, v210, v112
	v_mfma_f32_32x32x16_bf16 v[68:83], v[198:201], v[202:205], v[68:83]
	v_permlane32_swap_b32_e32 v103, v105
	v_add_f32_e32 v100, v212, v100
	v_add_f32_e32 v101, v213, v101
	s_waitcnt lgkmcnt(0)
	v_add_u32_e32 v197, v183, v174
	v_add_u32_e32 v198, v184, v174
	ds_read_b128 v[158:161], v197
	ds_read_b128 v[202:205], v198
	ds_read_b128 v[206:209], v169 offset:4096
	v_mfma_f32_32x32x16_bf16 v[84:99], v[134:137], v[154:157], v[84:99]
	v_add_f32_e32 v1, v215, v1
	v_cvt_pk_bf16_f32 v134, v220, v113
	v_add_f32_e32 v107, v214, v107
	v_mfma_f32_32x32x16_bf16 v[68:83], v[150:153], v[154:157], v[68:83]
	v_cvt_pk_bf16_f32 v135, v221, v222
	v_add_f32_e32 v100, v216, v100
	v_add_f32_e32 v101, v218, v101
	s_waitcnt lgkmcnt(0)
	v_add_u32_e32 v199, v183, v175
	v_add_u32_e32 v200, v184, v175
	ds_read_b128 v[150:153], v199
	ds_read_b128 v[154:157], v200
	ds_read_b128 v[210:213], v168 offset:4096
	v_mfma_f32_32x32x16_bf16 v[84:99], v[158:161], v[206:209], v[84:99]
	v_add_f32_e32 v1, v113, v1
	v_cvt_pk_bf16_f32 v136, v223, v226
	v_add_f32_e32 v107, v220, v107
	v_mfma_f32_32x32x16_bf16 v[68:83], v[202:205], v[206:209], v[68:83]
	v_cvt_pk_bf16_f32 v137, v227, v106
	v_add_f32_e32 v100, v221, v100
	v_add_f32_e32 v101, v222, v101
	s_waitcnt lgkmcnt(0)
	v_mfma_f32_32x32x16_bf16 v[84:99], v[150:153], v[210:213], v[84:99]
	v_add_f32_e32 v1, v226, v1
	v_permlane32_swap_b32_e32 v134, v136
	v_add_f32_e32 v107, v223, v107
	v_mfma_f32_32x32x16_bf16 v[68:83], v[154:157], v[210:213], v[68:83]
	v_permlane32_swap_b32_e32 v135, v137
	v_add_f32_e32 v100, v227, v100
	v_add_f32_e32 v101, v106, v101
	v_add_f32_e32 v1, v107, v1
	v_add_f32_e32 v100, v100, v101
	v_add_f32_e32 v201, v1, v100
	v_mov_b32_e32 v202, v201
	s_nop 1
	v_permlane32_swap_b32_e32 v201, v202

; #define SBAR() __builtin_amdgcn_sched_barrier(0)
; #define DMA_K(t, bf) do { if (ABL & 8) break; const char* kb_ = Kt + (size_t)(t) * KSTEP; LAS unsigned char* kd_ = Kl + (bf) * SHM_K + wid * 1024; \
;     glds16(kb_ + voffK, kd_); glds16(kb_ + 128 + voffK, kd_ + 8192); glds16(Pt + (size_t)(t) * PSTEP + voffP, kd_ + 16384); } while (0)
; #define DMA_V(t, bf) do { if (ABL & 8) break; const char* vb_ = Kt + 256 + (size_t)(t) * KSTEP; LAS unsigned char* vd_ = Vl + (bf) * SHM_V + wid * 1024; \
;     glds16(vb_ + voffV, vd_); glds16(vb_ + (size_t)32 * LDKV * 2 + voffV, vd_ + 8192); } while (0)
; #define END_STEP() do { if (!(ABL & 8)) { asm volatile("s_waitcnt vmcnt(0)" ::: "memory"); __syncthreads(); } } while (0)
; template <int ABL> __device__ __forceinline__ void attn_unit(int b, int h, int qb, const bf16_t* Q, const bf16_t* KV, const bf16_t* KPE, bf16_t* MG, float* ssqa, LAS unsigned char* L) {
;     ...
;     END_STEP(); DMA_K(j + 2, 1); DMA_V(j + 1, 0);
;     SBAR(); QK_TILE(Kl, pA0, pA1, pB0, pB1, alB, true);
.LBB0_759:
	v_lshl_add_u64 v[112:113], s[28:29], 0, v[146:147]
	s_mov_b64 s[54:55], 0x18fc0000
	s_mov_b32 m0, s78
	v_lshl_add_u64 v[100:101], v[112:113], 0, s[54:55]
	s_waitcnt vmcnt(0)
	s_barrier
	global_load_lds_dwordx4 v[100:101], off
	v_lshl_add_u64 v[100:101], v[112:113], 0, s[38:39]
	s_add_i32 m0, s78, 0x2000
	v_lshl_add_u64 v[136:137], s[28:29], 0, v[144:145]
	global_load_lds_dwordx4 v[100:101], off
	v_lshl_add_u64 v[100:101], v[136:137], 0, s[40:41]
	s_add_i32 m0, s78, 0x4000
	v_lshl_add_u64 v[134:135], s[28:29], 0, v[148:149]
	global_load_lds_dwordx4 v[100:101], off
	v_lshl_add_u64 v[100:101], v[134:135], 0, s[42:43]
	s_mov_b32 m0, s58
	global_load_lds_dwordx4 v[100:101], off
	v_lshl_add_u64 v[100:101], v[134:135], 0, s[44:45]
	s_mov_b32 m0, s77
	global_load_lds_dwordx4 v[100:101], off
	v_exp_f32_e32 v1, v246
	v_exp_f32_e32 v101, v84
	v_exp_f32_e32 v103, v85
	v_exp_f32_e32 v205, v89
	v_exp_f32_e32 v206, v90
	v_sub_f32_e32 v102, v70, v140
	v_sub_f32_e32 v204, v74, v140
	v_exp_f32_e32 v160, v88
	v_sub_f32_e32 v88, v69, v140
	v_sub_f32_e32 v158, v72, v140
	v_exp_f32_e32 v154, v86
	v_exp_f32_e32 v159, v87
	v_exp_f32_e32 v208, v91
	v_exp_f32_e32 v209, v92
	v_exp_f32_e32 v210, v93
	v_exp_f32_e32 v211, v94
	v_sub_f32_e32 v155, v71, v140
	v_sub_f32_e32 v161, v73, v140
	v_sub_f32_e32 v207, v75, v140
	ds_read_b128 v[68:71], v178 offset:32768
	ds_read_b128 v[84:87], v178 offset:36864
	s_waitcnt lgkmcnt(0)
	ds_read_b128 v[104:107], v179 offset:32768
	ds_read_b128 v[108:111], v179 offset:36864
	v_mfma_f32_32x32x16_bf16 v[68:83], v[68:71], v[126:129], 0
	v_cvt_pk_bf16_f32 v100, v1, v101
	v_exp_f32_e32 v226, v99
	v_add_f32_e32 v227, 0, v1
	v_exp_f32_e32 v1, v88
	v_mfma_f32_32x32x16_bf16 v[84:99], v[84:87], v[126:129], 0
	v_add_f32_e32 v228, 0, v101
	v_cvt_pk_bf16_f32 v101, v103, v154
	s_waitcnt lgkmcnt(0)
	ds_read_b128 v[130:133], v177 offset:32768
	ds_read_b128 v[150:153], v177 offset:36864
	v_mfma_f32_32x32x16_bf16 v[68:83], v[104:107], v[122:125], v[68:83]
	v_exp_f32_e32 v229, v102
	v_cvt_pk_bf16_f32 v102, v159, v160
	v_add_f32_e32 v230, 0, v103
	v_mfma_f32_32x32x16_bf16 v[84:99], v[108:111], v[122:125], v[84:99]
	v_add_f32_e32 v105, 0, v154
	v_cvt_pk_bf16_f32 v103, v205, v206
	v_exp_f32_e32 v231, v155
	s_waitcnt lgkmcnt(0)
	ds_read_b128 v[106:109], v176 offset:32768
	ds_read_b128 v[154:157], v176 offset:36864
	v_mfma_f32_32x32x16_bf16 v[68:83], v[130:133], v[118:121], v[68:83]
	v_permlane32_swap_b32_e32 v100, v102
	v_exp_f32_e32 v232, v158
	v_add_f32_e32 v227, v159, v227
	v_mfma_f32_32x32x16_bf16 v[84:99], v[150:153], v[118:121], v[84:99]
	v_permlane32_swap_b32_e32 v101, v103
	v_exp_f32_e32 v233, v161
	v_add_f32_e32 v228, v160, v228
	s_waitcnt lgkmcnt(0)
	ds_read_b128 v[130:133], v178 offset:40960
	ds_read_b128 v[150:153], v178 offset:45056
	v_mfma_f32_32x32x16_bf16 v[68:83], v[106:109], v[114:117], v[68:83]
	v_cvt_pk_bf16_f32 v104, v208, v209
	v_exp_f32_e32 v234, v204
	v_add_f32_e32 v230, v205, v230
	v_mfma_f32_32x32x16_bf16 v[84:99], v[154:157], v[114:117], v[84:99]
	v_add_f32_e32 v236, v206, v105
	v_cvt_pk_bf16_f32 v105, v210, v211
	v_exp_f32_e32 v235, v207
	s_waitcnt lgkmcnt(0)
	ds_read_b128 v[108:111], v179 offset:40960
	ds_read_b128 v[154:157], v179 offset:45056
	v_mfma_f32_32x32x16_bf16 v[68:83], v[130:133], v[238:241], v[68:83]
	v_cvt_pk_bf16_f32 v106, v212, v213
	v_exp_f32_e32 v216, v216
	v_add_f32_e32 v227, v208, v227
	v_mfma_f32_32x32x16_bf16 v[84:99], v[150:153], v[238:241], v[84:99]
	v_cvt_pk_bf16_f32 v107, v214, v215
	v_exp_f32_e32 v217, v217
	v_add_f32_e32 v228, v209, v228
	s_waitcnt lgkmcnt(0)
	ds_read_b128 v[130:133], v177 offset:40960
	ds_read_b128 v[150:153], v177 offset:45056
	v_mfma_f32_32x32x16_bf16 v[68:83], v[108:111], v[242:245], v[68:83]
	v_permlane32_swap_b32_e32 v104, v106
	v_exp_f32_e32 v218, v218
	v_add_f32_e32 v230, v210, v230
	v_mfma_f32_32x32x16_bf16 v[84:99], v[154:157], v[242:245], v[84:99]
	v_add_f32_e32 v111, v211, v236
	v_permlane32_swap_b32_e32 v105, v107
	v_exp_f32_e32 v219, v219
	s_waitcnt lgkmcnt(0)
	ds_read_b128 v[154:157], v176 offset:40960
	ds_read_b128 v[204:207], v176 offset:45056
	v_mfma_f32_32x32x16_bf16 v[68:83], v[130:133], v[248:251], v[68:83]
	v_cvt_pk_bf16_f32 v108, v226, v1
	v_exp_f32_e32 v220, v220
	v_add_f32_e32 v212, v212, v227
	v_mfma_f32_32x32x16_bf16 v[84:99], v[150:153], v[248:251], v[84:99]
	v_cvt_pk_bf16_f32 v109, v229, v231
	v_exp_f32_e32 v221, v221
	v_add_f32_e32 v213, v213, v228
	s_waitcnt lgkmcnt(0)
	ds_read_b128 v[130:133], v178 offset:49152
	ds_read_b128 v[150:153], v178 offset:53248
	ds_read_b128 v[158:161], v171 offset:4096
	v_mfma_f32_32x32x16_bf16 v[68:83], v[154:157], v[252:255], v[68:83]
	v_cvt_pk_bf16_f32 v110, v232, v233
	v_exp_f32_e32 v222, v222
	v_add_f32_e32 v214, v214, v230
	v_mfma_f32_32x32x16_bf16 v[84:99], v[204:207], v[252:255], v[84:99]
	v_add_f32_e32 v215, v215, v111
	v_cvt_pk_bf16_f32 v111, v234, v235
	v_exp_f32_e32 v223, v223
	s_waitcnt lgkmcnt(0)
	ds_read_b128 v[154:157], v179 offset:49152
	ds_read_b128 v[204:207], v179 offset:53248
	ds_read_b128 v[208:211], v170 offset:4096
	v_mfma_f32_32x32x16_bf16 v[68:83], v[130:133], v[158:161], v[68:83]
	v_add_f32_e32 v1, v1, v213
	v_permlane32_swap_b32_e32 v108, v110
	v_add_f32_e32 v226, v226, v212
	v_mfma_f32_32x32x16_bf16 v[84:99], v[150:153], v[158:161], v[84:99]
	v_add_f32_e32 v131, v229, v214
	v_add_f32_e32 v132, v231, v215
	v_permlane32_swap_b32_e32 v109, v111
	s_waitcnt lgkmcnt(0)
	ds_read_b128 v[150:153], v177 offset:49152
	ds_read_b128 v[158:161], v177 offset:53248
	ds_read_b128 v[212:215], v169 offset:4096
	v_mfma_f32_32x32x16_bf16 v[68:83], v[154:157], v[208:211], v[68:83]
	v_add_f32_e32 v133, v232, v226
	v_add_f32_e32 v1, v233, v1
	v_cvt_pk_bf16_f32 v130, v216, v217
	v_mfma_f32_32x32x16_bf16 v[84:99], v[204:207], v[208:211], v[84:99]
	v_add_f32_e32 v226, v234, v131
	v_cvt_pk_bf16_f32 v131, v218, v219
	v_add_f32_e32 v227, v235, v132
	s_waitcnt lgkmcnt(0)
	ds_read_b128 v[154:157], v176 offset:49152
	ds_read_b128 v[204:207], v176 offset:53248
	ds_read_b128 v[208:211], v168 offset:4096
	v_mfma_f32_32x32x16_bf16 v[68:83], v[150:153], v[212:215], v[68:83]
	v_add_f32_e32 v1, v217, v1
	v_cvt_pk_bf16_f32 v132, v220, v221
	v_add_f32_e32 v216, v216, v133
	v_mfma_f32_32x32x16_bf16 v[84:99], v[158:161], v[212:215], v[84:99]
	v_cvt_pk_bf16_f32 v133, v222, v223
	v_add_f32_e32 v150, v218, v226
	v_add_f32_e32 v151, v219, v227
	s_waitcnt lgkmcnt(0)
	v_mfma_f32_32x32x16_bf16 v[68:83], v[154:157], v[208:211], v[68:83]
	v_add_f32_e32 v1, v221, v1
	v_permlane32_swap_b32_e32 v130, v132
	v_add_f32_e32 v152, v220, v216
	v_mfma_f32_32x32x16_bf16 v[84:99], v[204:207], v[208:211], v[84:99]
	v_permlane32_swap_b32_e32 v131, v133
	v_add_f32_e32 v150, v222, v150
	v_add_f32_e32 v151, v223, v151
	v_add_f32_e32 v1, v152, v1
	v_add_f32_e32 v150, v150, v151
	v_add_f32_e32 v205, v1, v150
	v_mov_b32_e32 v206, v205
	s_nop 1
	v_permlane32_swap_b32_e32 v205, v206
